# v45 + attention phases P4/P5: one static s_setprio 1 for waves 0-3 (the other half than v44) at phase entry, reset at P6
# baseline (speedup 1.0000x reference)
; #define LAS __attribute__((address_space(3)))
; __device__ __forceinline__ ArgsP get_args() { unsigned long long p = (unsigned long long)__builtin_amdgcn_kernarg_segment_ptr(); asm volatile("" : "+s"(p)); return (ArgsP)p; }
; __global__ void __launch_bounds__(NWAVES * 64, 2) mk_fwd(Args args) {
;     ...
;     if (IN(4)) { a = get_args();
;         if (MK_DBG & 8) { for (int u = 135168 / 4 + F.tid; u < LDS_BYTES / 4; u += NWAVES * 64) ((LAS unsigned*)F.lds)[u] = 0u; __syncthreads(); }
;         if (MK_DBG & 16) { for (int q = 0; q < 64; ++q) __builtin_amdgcn_s_sleep(64); }
;         if (MK_ATTN & 1) {
.LBB0_512:
	v_readlane_b32 s2, v254, 11
	v_readlane_b32 s3, v254, 12
	s_cmp_lt_i32 s2, 5
	s_cselect_b64 s[2:3], -1, 0
	s_and_b64 s[0:1], s[2:3], s[0:1]
	v_writelane_b32 v254, s0, 15
	s_andn2_b64 vcc, exec, s[0:1]
	s_nop 0
	v_writelane_b32 v254, s1, 16
	v_writelane_b32 v254, s74, 17
	s_cbranch_vccnz .LBB0_1158
	v_readlane_b32 s98, v254, 10
	s_cmp_gt_u32 s98, 3
	s_cbranch_scc1 .Lsp_attn
	s_setprio 1
